# hotdummy: P7 last-iteration dummy staging loads of a workgroup's final unit re-read the unit's last two K tiles (L2-hot) instead of its first two
# baseline (speedup 1.0000x reference)
;     __host__ __device__ bool next(int i, Unit& u) const { return at((long)i * G + c, u); }
;     __host__ __device__ bool next(int i, Unit& u) const { if (i != 0 || c >= cnt) return false; u.pm = pm0 + c / nN; u.pn = c % nN; u.k0 = 0; u.nt = ntk; return true; }
;     ...
;         const bool has_next = S.next(ui + 1, nxt);
;         const char* nA = has_next ? (const char*)g.A + (size_t)nxt.pm * tstep + (size_t)nxt.k0 * (BK * 2) : cA; const char* nB = has_next ? (const char*)g.Bt + (size_t)nxt.pn * tstep + (size_t)nxt.k0 * (BK * 2) : cB;
;         const int nt = cur.nt;
;         for (int t = 0; t < nt; t += 2) {
;             const bool last = (t == nt - 2);
;             const char* a1 = cA + (size_t)(t + 1) * kstep;
;             const char* a2 = last ? nA : cA + (size_t)(t + 2) * kstep; const char* b2 = last ? nB : cB + (size_t)(t + 2) * kstep;
;             const char* a3 = a2 + kstep; const char* b3 = b2 + kstep;
.LBB0_1053:
	s_ashr_i32 s23, s22, 31
	s_xor_b64 s[28:29], s[40:41], -1
	s_lshl_b64 s[30:31], s[22:23], 21
	s_add_u32 s13, s4, s30
	s_addc_u32 s23, s5, s31
	s_ashr_i32 s27, s26, 31
	s_lshl_b64 s[34:35], s[26:27], 7
	s_add_u32 s30, s13, s34
	s_addc_u32 s31, s23, s35
	s_add_u32 s42, s38, 0x1f00
	s_addc_u32 s43, s39, 0
	s_cmp_lg_u64 s[40:41], 0
	s_cselect_b32 s13, s31, s43
	s_cselect_b32 s23, s30, s42
	s_ashr_i32 s25, s24, 31
	s_lshl_b64 s[42:43], s[24:25], 21
	s_add_u32 s25, s3, s42
	s_addc_u32 s27, s47, s43
	s_add_u32 s34, s25, s34
	s_addc_u32 s35, s27, s35
	s_add_u32 s42, s36, 0x1f00
	s_addc_u32 s43, s37, 0
	s_cmp_lg_u64 s[40:41], 0
	s_cselect_b32 s25, s35, s43
	s_cselect_b32 s27, s34, s42
	s_mov_b32 s73, 2
	s_mov_b64 s[42:43], 0x100
	v_mov_b64_e32 v[130:131], v[144:145]
	v_mov_b64_e32 v[150:151], v[142:143]
	s_cmp_lg_u32 s100, 0
	s_cbranch_scc1 .Lnb8_m
	v_readlane_b32 s98, v255, 14
	s_lshr_b32 s98, s98, 6
	s_cmp_lg_u32 s98, 16
	s_cbranch_scc1 .Lnb8_m
	v_readlane_b32 s98, v255, 13
	s_cmp_lg_u32 s98, 0
	s_cbranch_scc1 .Lnb8_m
	s_mov_b32 s99, 0x7777
	s_mov_b32 s101, 0x9999
